# grid barrier leader: XGEN release atomic issued before the leader's own acquire invalidate (same fences, shorter release chain for the other WGs of the XCD)
# baseline (speedup 1.0000x reference)
; __device__ __forceinline__ unsigned xb_ld(unsigned* p)              { return __hip_atomic_load(p, __ATOMIC_RELAXED, __HIP_MEMORY_SCOPE_AGENT); }
; __device__ __forceinline__ unsigned xb_add(unsigned* p, unsigned v) { return __hip_atomic_fetch_add(p, v, __ATOMIC_RELAXED, __HIP_MEMORY_SCOPE_AGENT); }
; #define XB_SPIN(cond, bar) do { unsigned _sp = 0; while (cond) { __builtin_amdgcn_s_sleep(1); \
;     if ((++_sp & 255u) == 0u) { if (xb_ld(&(bar)[XB_TMO])) break; if (_sp > XB_SPIN_CAP) { atomicAdd(&(bar)[XB_TMO], 1u); break; } } } } while (0)
; __device__ __forceinline__ void xcd_barrier(const XcdBarrier& b) {
;     ...
;             __builtin_amdgcn_fence(__ATOMIC_RELEASE, "agent");
;             asm volatile("s_waitcnt vmcnt(0)" ::: "memory");
;             const unsigned og = xb_add(&bar[XB_TOP], 1u);
;             const unsigned tg = og / nx;
;             if (og + 1u == (tg + 1u) * nx) xb_add(&bar[XB_TOPGEN], 1u);
;             else XB_SPIN(xb_ld(&bar[XB_TOPGEN]) == tg, bar);
;             __builtin_amdgcn_fence(__ATOMIC_ACQUIRE, "agent");
;             xb_add(&bar[XB_XGEN(b.x)], 1u);
;             asm volatile("s_waitcnt vmcnt(0)" ::: "memory");
.LBB0_378:
	s_or_b64 exec, exec, s[2:3]
	v_readlane_b32 s2, v253, 6
	v_readlane_b32 s3, v253, 7
	s_waitcnt vmcnt(0)
	s_nop 2
	global_atomic_add v1, v209, s[2:3]
	buffer_inv sc1
	s_waitcnt vmcnt(0)
